# MFMA pair order: weight fragment held across four accumulate pairs (n-major snake)
# baseline (speedup 1.0000x reference)
.LBB0_169:
	s_add_u32 s34, s50, 0xfff80080
	s_addc_u32 s35, s51, -1
	s_add_i32 s52, 0, 0x10000
	s_cmp_eq_u32 s77, 28
	s_cselect_b32 s55, s36, s35
	s_cselect_b32 s54, s37, s34
	v_add_u32_e32 v145, s52, v142
	s_cselect_b32 s35, s41, s76
	s_cselect_b32 s34, s43, s71
	s_add_i32 s53, 0, 0x14000
	ds_read_b128 v[146:149], v145
	ds_read_b128 v[150:153], v145 offset:1024
	ds_read_b128 v[172:175], v145 offset:2048
	ds_read_b128 v[176:179], v145 offset:3072
	v_add_u32_e32 v145, s53, v142
	ds_read_b128 v[180:183], v145
	ds_read_b128 v[184:187], v145 offset:1024
	ds_read_b128 v[188:191], v145 offset:2048
	ds_read_b128 v[192:195], v145 offset:3072
	v_lshl_add_u64 v[154:155], s[50:51], 0, v[138:139]
	s_add_i32 m0, s57, 0xc000
	ds_read_b128 v[196:199], v144
	ds_read_b128 v[200:203], v144 offset:1024
	ds_read_b128 v[204:207], v144 offset:2048
	ds_read_b128 v[208:211], v144 offset:3072
	ds_read_b128 v[212:215], v144 offset:4096
	ds_read_b128 v[216:219], v144 offset:5120
	ds_read_b128 v[228:231], v144 offset:6144
	ds_read_b128 v[232:235], v144 offset:7168
	global_load_lds_dwordx4 v[154:155], off
	v_lshl_add_u64 v[154:155], s[50:51], 0, v[140:141]
	s_add_i32 m0, s57, 0xe000
	s_nop 0
	global_load_lds_dwordx4 v[154:155], off
	s_waitcnt vmcnt(8)
	s_waitcnt lgkmcnt(0)
	s_barrier
	s_setprio 1
	v_mfma_f32_16x16x32_bf16 v[128:131], v[146:149], v[196:199], v[128:131]
	v_mfma_f32_16x16x32_bf16 v[128:131], v[150:153], v[200:203], v[128:131]
	v_mfma_f32_16x16x32_bf16 v[112:115], v[146:149], v[204:207], v[112:115]
	v_mfma_f32_16x16x32_bf16 v[112:115], v[150:153], v[208:211], v[112:115]
	v_mfma_f32_16x16x32_bf16 v[96:99], v[146:149], v[212:215], v[96:99]
	v_mfma_f32_16x16x32_bf16 v[96:99], v[150:153], v[216:219], v[96:99]
	v_mfma_f32_16x16x32_bf16 v[80:83], v[146:149], v[228:231], v[80:83]
	v_mfma_f32_16x16x32_bf16 v[80:83], v[150:153], v[232:235], v[80:83]
	v_mfma_f32_16x16x32_bf16 v[76:79], v[172:175], v[228:231], v[76:79]
	v_mfma_f32_16x16x32_bf16 v[76:79], v[176:179], v[232:235], v[76:79]
	v_mfma_f32_16x16x32_bf16 v[92:95], v[172:175], v[212:215], v[92:95]
	v_mfma_f32_16x16x32_bf16 v[92:95], v[176:179], v[216:219], v[92:95]
	v_mfma_f32_16x16x32_bf16 v[108:111], v[172:175], v[204:207], v[108:111]
	v_mfma_f32_16x16x32_bf16 v[108:111], v[176:179], v[208:211], v[108:111]
	v_mfma_f32_16x16x32_bf16 v[124:127], v[172:175], v[196:199], v[124:127]
	v_mfma_f32_16x16x32_bf16 v[124:127], v[176:179], v[200:203], v[124:127]
	v_mfma_f32_16x16x32_bf16 v[120:123], v[180:183], v[196:199], v[120:123]
	v_mfma_f32_16x16x32_bf16 v[120:123], v[184:187], v[200:203], v[120:123]
	v_mfma_f32_16x16x32_bf16 v[104:107], v[180:183], v[204:207], v[104:107]
	v_mfma_f32_16x16x32_bf16 v[104:107], v[184:187], v[208:211], v[104:107]
	v_mfma_f32_16x16x32_bf16 v[88:91], v[180:183], v[212:215], v[88:91]
	v_mfma_f32_16x16x32_bf16 v[88:91], v[184:187], v[216:219], v[88:91]
	v_mfma_f32_16x16x32_bf16 v[72:75], v[180:183], v[228:231], v[72:75]
	v_mfma_f32_16x16x32_bf16 v[72:75], v[184:187], v[232:235], v[72:75]
	v_mfma_f32_16x16x32_bf16 v[68:71], v[188:191], v[228:231], v[68:71]
	v_mfma_f32_16x16x32_bf16 v[68:71], v[192:195], v[232:235], v[68:71]
	v_mfma_f32_16x16x32_bf16 v[84:87], v[188:191], v[212:215], v[84:87]
	v_mfma_f32_16x16x32_bf16 v[84:87], v[192:195], v[216:219], v[84:87]
	v_mfma_f32_16x16x32_bf16 v[100:103], v[188:191], v[204:207], v[100:103]
	v_mfma_f32_16x16x32_bf16 v[100:103], v[192:195], v[208:211], v[100:103]
	v_mfma_f32_16x16x32_bf16 v[116:119], v[188:191], v[196:199], v[116:119]
	v_mfma_f32_16x16x32_bf16 v[116:119], v[192:195], v[200:203], v[116:119]
	s_setprio 0
	s_barrier
	s_add_i32 s52, s52, s19
	v_lshl_add_u64 v[154:155], s[34:35], 0, v[134:135]
	s_mov_b32 m0, s52
	ds_read_b128 v[196:199], v144 offset:16384
	ds_read_b128 v[200:203], v144 offset:17408
	ds_read_b128 v[204:207], v144 offset:18432
	ds_read_b128 v[208:211], v144 offset:19456
	ds_read_b128 v[212:215], v144 offset:20480
	ds_read_b128 v[216:219], v144 offset:21504
	ds_read_b128 v[228:231], v144 offset:22528
	ds_read_b128 v[232:235], v144 offset:23552
	global_load_lds_dwordx4 v[154:155], off
	s_add_i32 m0, s52, 0x2000
	s_add_u32 s96, s34, 0x4000
	v_lshl_add_u64 v[154:155], s[34:35], 0, v[0:1]
	s_addc_u32 s97, s35, 0
	s_add_i32 s52, s53, s19
	global_load_lds_dwordx4 v[154:155], off
	v_lshl_add_u64 v[154:155], s[96:97], 0, v[134:135]
	s_mov_b32 m0, s52
	v_lshl_add_u64 v[236:237], s[54:55], 0, v[132:133]
	global_load_lds_dwordx4 v[154:155], off
	v_lshl_add_u64 v[154:155], s[96:97], 0, v[0:1]
	s_add_i32 m0, s52, 0x2000
	s_nop 0
	global_load_lds_dwordx4 v[154:155], off
	v_lshl_add_u64 v[154:155], s[54:55], 0, v[136:137]
	s_mov_b32 m0, s57
	s_nop 0
	global_load_lds_dwordx4 v[154:155], off
	s_mov_b32 m0, s58
	s_nop 0
	global_load_lds_dwordx4 v[236:237], off
	s_waitcnt vmcnt(8)
	s_waitcnt lgkmcnt(0)
	s_barrier
	s_setprio 1
	v_mfma_f32_16x16x32_bf16 v[64:67], v[146:149], v[196:199], v[64:67]
	v_mfma_f32_16x16x32_bf16 v[64:67], v[150:153], v[200:203], v[64:67]
	v_mfma_f32_16x16x32_bf16 v[48:51], v[146:149], v[204:207], v[48:51]
	v_mfma_f32_16x16x32_bf16 v[48:51], v[150:153], v[208:211], v[48:51]
	v_mfma_f32_16x16x32_bf16 v[32:35], v[146:149], v[212:215], v[32:35]
	v_mfma_f32_16x16x32_bf16 v[32:35], v[150:153], v[216:219], v[32:35]
	v_mfma_f32_16x16x32_bf16 v[16:19], v[146:149], v[228:231], v[16:19]
	v_mfma_f32_16x16x32_bf16 v[16:19], v[150:153], v[232:235], v[16:19]
	v_mfma_f32_16x16x32_bf16 v[12:15], v[172:175], v[228:231], v[12:15]
	v_mfma_f32_16x16x32_bf16 v[12:15], v[176:179], v[232:235], v[12:15]
	v_mfma_f32_16x16x32_bf16 v[28:31], v[172:175], v[212:215], v[28:31]
	v_mfma_f32_16x16x32_bf16 v[28:31], v[176:179], v[216:219], v[28:31]
	v_mfma_f32_16x16x32_bf16 v[44:47], v[172:175], v[204:207], v[44:47]
	v_mfma_f32_16x16x32_bf16 v[44:47], v[176:179], v[208:211], v[44:47]
	v_mfma_f32_16x16x32_bf16 v[60:63], v[172:175], v[196:199], v[60:63]
	v_mfma_f32_16x16x32_bf16 v[60:63], v[176:179], v[200:203], v[60:63]
	v_mfma_f32_16x16x32_bf16 v[56:59], v[180:183], v[196:199], v[56:59]
	v_mfma_f32_16x16x32_bf16 v[56:59], v[184:187], v[200:203], v[56:59]
	v_mfma_f32_16x16x32_bf16 v[40:43], v[180:183], v[204:207], v[40:43]
	v_mfma_f32_16x16x32_bf16 v[40:43], v[184:187], v[208:211], v[40:43]
	v_mfma_f32_16x16x32_bf16 v[24:27], v[180:183], v[212:215], v[24:27]
	v_mfma_f32_16x16x32_bf16 v[24:27], v[184:187], v[216:219], v[24:27]
	v_mfma_f32_16x16x32_bf16 v[8:11], v[180:183], v[228:231], v[8:11]
	v_mfma_f32_16x16x32_bf16 v[8:11], v[184:187], v[232:235], v[8:11]
	v_mfma_f32_16x16x32_bf16 v[4:7], v[188:191], v[228:231], v[4:7]
	v_mfma_f32_16x16x32_bf16 v[4:7], v[192:195], v[232:235], v[4:7]
	v_mfma_f32_16x16x32_bf16 v[20:23], v[188:191], v[212:215], v[20:23]
	v_mfma_f32_16x16x32_bf16 v[20:23], v[192:195], v[216:219], v[20:23]
	v_mfma_f32_16x16x32_bf16 v[36:39], v[188:191], v[204:207], v[36:39]
	v_mfma_f32_16x16x32_bf16 v[36:39], v[192:195], v[208:211], v[36:39]
	v_mfma_f32_16x16x32_bf16 v[52:55], v[188:191], v[196:199], v[52:55]
	v_mfma_f32_16x16x32_bf16 v[52:55], v[192:195], v[200:203], v[52:55]
	s_setprio 0
	s_barrier
	s_add_i32 s52, 0, 0x18000
	v_add_u32_e32 v145, s52, v142
	s_add_i32 s53, 0, 0x1c000
	ds_read_b128 v[146:149], v145
	ds_read_b128 v[150:153], v145 offset:1024
	ds_read_b128 v[172:175], v145 offset:2048
	ds_read_b128 v[176:179], v145 offset:3072
	v_add_u32_e32 v145, s53, v142
	ds_read_b128 v[180:183], v145
	ds_read_b128 v[184:187], v145 offset:1024
	ds_read_b128 v[188:191], v145 offset:2048
	ds_read_b128 v[192:195], v145 offset:3072
	s_add_u32 s54, s54, 0x80000
	s_addc_u32 s55, s55, 0
	s_mov_b32 m0, s59
	v_lshl_add_u64 v[238:239], s[54:55], 0, v[136:137]
	ds_read_b128 v[196:199], v144 offset:32768
	ds_read_b128 v[200:203], v144 offset:33792
	ds_read_b128 v[204:207], v144 offset:34816
	ds_read_b128 v[208:211], v144 offset:35840
	ds_read_b128 v[212:215], v144 offset:36864
	ds_read_b128 v[216:219], v144 offset:37888
	ds_read_b128 v[228:231], v144 offset:38912
	ds_read_b128 v[232:235], v144 offset:39936
	global_load_lds_dwordx4 v[238:239], off
	v_lshl_add_u64 v[238:239], s[54:55], 0, v[132:133]
	s_mov_b32 m0, s60
	s_nop 0
	global_load_lds_dwordx4 v[238:239], off
	s_waitcnt vmcnt(8)
	s_waitcnt lgkmcnt(0)
	s_barrier
	s_setprio 1
	v_mfma_f32_16x16x32_bf16 v[128:131], v[146:149], v[196:199], v[128:131]
	v_mfma_f32_16x16x32_bf16 v[128:131], v[150:153], v[200:203], v[128:131]
	v_mfma_f32_16x16x32_bf16 v[112:115], v[146:149], v[204:207], v[112:115]
	v_mfma_f32_16x16x32_bf16 v[112:115], v[150:153], v[208:211], v[112:115]
	v_mfma_f32_16x16x32_bf16 v[96:99], v[146:149], v[212:215], v[96:99]
	v_mfma_f32_16x16x32_bf16 v[96:99], v[150:153], v[216:219], v[96:99]
	v_mfma_f32_16x16x32_bf16 v[80:83], v[146:149], v[228:231], v[80:83]
	v_mfma_f32_16x16x32_bf16 v[80:83], v[150:153], v[232:235], v[80:83]
	v_mfma_f32_16x16x32_bf16 v[76:79], v[172:175], v[228:231], v[76:79]
	v_mfma_f32_16x16x32_bf16 v[76:79], v[176:179], v[232:235], v[76:79]
	v_mfma_f32_16x16x32_bf16 v[92:95], v[172:175], v[212:215], v[92:95]
	v_mfma_f32_16x16x32_bf16 v[92:95], v[176:179], v[216:219], v[92:95]
	v_mfma_f32_16x16x32_bf16 v[108:111], v[172:175], v[204:207], v[108:111]
	v_mfma_f32_16x16x32_bf16 v[108:111], v[176:179], v[208:211], v[108:111]
	v_mfma_f32_16x16x32_bf16 v[124:127], v[172:175], v[196:199], v[124:127]
	v_mfma_f32_16x16x32_bf16 v[124:127], v[176:179], v[200:203], v[124:127]
	v_mfma_f32_16x16x32_bf16 v[120:123], v[180:183], v[196:199], v[120:123]
	v_mfma_f32_16x16x32_bf16 v[120:123], v[184:187], v[200:203], v[120:123]
	v_mfma_f32_16x16x32_bf16 v[104:107], v[180:183], v[204:207], v[104:107]
	v_mfma_f32_16x16x32_bf16 v[104:107], v[184:187], v[208:211], v[104:107]
	v_mfma_f32_16x16x32_bf16 v[88:91], v[180:183], v[212:215], v[88:91]
	v_mfma_f32_16x16x32_bf16 v[88:91], v[184:187], v[216:219], v[88:91]
	v_mfma_f32_16x16x32_bf16 v[72:75], v[180:183], v[228:231], v[72:75]
	v_mfma_f32_16x16x32_bf16 v[72:75], v[184:187], v[232:235], v[72:75]
	v_mfma_f32_16x16x32_bf16 v[68:71], v[188:191], v[228:231], v[68:71]
	v_mfma_f32_16x16x32_bf16 v[68:71], v[192:195], v[232:235], v[68:71]
	v_mfma_f32_16x16x32_bf16 v[84:87], v[188:191], v[212:215], v[84:87]
	v_mfma_f32_16x16x32_bf16 v[84:87], v[192:195], v[216:219], v[84:87]
	v_mfma_f32_16x16x32_bf16 v[100:103], v[188:191], v[204:207], v[100:103]
	v_mfma_f32_16x16x32_bf16 v[100:103], v[192:195], v[208:211], v[100:103]
	v_mfma_f32_16x16x32_bf16 v[116:119], v[188:191], v[196:199], v[116:119]
	v_mfma_f32_16x16x32_bf16 v[116:119], v[192:195], v[200:203], v[116:119]
	s_setprio 0
	s_barrier
	s_add_u32 s54, s34, 0x160000
	s_addc_u32 s55, s35, 0
	s_add_i32 s52, s52, s19
	v_lshl_add_u64 v[238:239], s[54:55], 0, v[134:135]
	s_mov_b32 m0, s52
	ds_read_b128 v[196:199], v144 offset:49152
	ds_read_b128 v[200:203], v144 offset:50176
	ds_read_b128 v[204:207], v144 offset:51200
	ds_read_b128 v[208:211], v144 offset:52224
	ds_read_b128 v[212:215], v144 offset:53248
	ds_read_b128 v[216:219], v144 offset:54272
	ds_read_b128 v[228:231], v144 offset:55296
	ds_read_b128 v[232:235], v144 offset:56320
	global_load_lds_dwordx4 v[238:239], off
	s_add_i32 m0, s52, 0x2000
	s_add_u32 s34, s34, 0x164000
	v_lshl_add_u64 v[238:239], s[54:55], 0, v[0:1]
	s_addc_u32 s35, s35, 0
	s_add_i32 s52, s53, s19
	global_load_lds_dwordx4 v[238:239], off
	v_lshl_add_u64 v[238:239], s[34:35], 0, v[134:135]
	s_mov_b32 m0, s52
	v_lshl_add_u64 v[154:155], v[154:155], 0, s[14:15]
	global_load_lds_dwordx4 v[238:239], off
	v_lshl_add_u64 v[238:239], s[34:35], 0, v[0:1]
	s_add_i32 m0, s52, 0x2000
	s_nop 0
	global_load_lds_dwordx4 v[238:239], off
	s_mov_b32 m0, s61
	s_nop 0
	global_load_lds_dwordx4 v[154:155], off
	v_lshl_add_u64 v[154:155], v[236:237], 0, s[14:15]
	s_mov_b32 m0, s62
	s_nop 0
	global_load_lds_dwordx4 v[154:155], off
	s_waitcnt vmcnt(8)
	s_waitcnt lgkmcnt(0)
	s_barrier
	s_setprio 1
	v_mfma_f32_16x16x32_bf16 v[64:67], v[146:149], v[196:199], v[64:67]
	v_mfma_f32_16x16x32_bf16 v[64:67], v[150:153], v[200:203], v[64:67]
	v_mfma_f32_16x16x32_bf16 v[48:51], v[146:149], v[204:207], v[48:51]
	v_mfma_f32_16x16x32_bf16 v[48:51], v[150:153], v[208:211], v[48:51]
	v_mfma_f32_16x16x32_bf16 v[32:35], v[146:149], v[212:215], v[32:35]
	v_mfma_f32_16x16x32_bf16 v[32:35], v[150:153], v[216:219], v[32:35]
	v_mfma_f32_16x16x32_bf16 v[16:19], v[146:149], v[228:231], v[16:19]
	v_mfma_f32_16x16x32_bf16 v[16:19], v[150:153], v[232:235], v[16:19]
	v_mfma_f32_16x16x32_bf16 v[12:15], v[172:175], v[228:231], v[12:15]
	v_mfma_f32_16x16x32_bf16 v[12:15], v[176:179], v[232:235], v[12:15]
	v_mfma_f32_16x16x32_bf16 v[28:31], v[172:175], v[212:215], v[28:31]
	v_mfma_f32_16x16x32_bf16 v[28:31], v[176:179], v[216:219], v[28:31]
	v_mfma_f32_16x16x32_bf16 v[44:47], v[172:175], v[204:207], v[44:47]
	v_mfma_f32_16x16x32_bf16 v[44:47], v[176:179], v[208:211], v[44:47]
	v_mfma_f32_16x16x32_bf16 v[60:63], v[172:175], v[196:199], v[60:63]
	v_mfma_f32_16x16x32_bf16 v[60:63], v[176:179], v[200:203], v[60:63]
	v_mfma_f32_16x16x32_bf16 v[56:59], v[180:183], v[196:199], v[56:59]
	v_mfma_f32_16x16x32_bf16 v[56:59], v[184:187], v[200:203], v[56:59]
	v_mfma_f32_16x16x32_bf16 v[40:43], v[180:183], v[204:207], v[40:43]
	v_mfma_f32_16x16x32_bf16 v[40:43], v[184:187], v[208:211], v[40:43]
	v_mfma_f32_16x16x32_bf16 v[24:27], v[180:183], v[212:215], v[24:27]
	v_mfma_f32_16x16x32_bf16 v[24:27], v[184:187], v[216:219], v[24:27]
	v_mfma_f32_16x16x32_bf16 v[8:11], v[180:183], v[228:231], v[8:11]
	v_mfma_f32_16x16x32_bf16 v[8:11], v[184:187], v[232:235], v[8:11]
	v_mfma_f32_16x16x32_bf16 v[4:7], v[188:191], v[228:231], v[4:7]
	v_mfma_f32_16x16x32_bf16 v[4:7], v[192:195], v[232:235], v[4:7]
	v_mfma_f32_16x16x32_bf16 v[20:23], v[188:191], v[212:215], v[20:23]
	v_mfma_f32_16x16x32_bf16 v[20:23], v[192:195], v[216:219], v[20:23]
	v_mfma_f32_16x16x32_bf16 v[36:39], v[188:191], v[204:207], v[36:39]
	v_mfma_f32_16x16x32_bf16 v[36:39], v[192:195], v[208:211], v[36:39]
	v_mfma_f32_16x16x32_bf16 v[52:55], v[188:191], v[196:199], v[52:55]
	v_mfma_f32_16x16x32_bf16 v[52:55], v[192:195], v[200:203], v[52:55]
	s_setprio 0
	s_barrier
	s_add_i32 s77, s77, 2
	s_add_u32 s71, s71, 0x2c0000
	s_addc_u32 s76, s76, 0
	s_add_u32 s50, s50, 0x100
	s_addc_u32 s51, s51, 0
	s_cmp_gt_u32 s77, 29
	s_cbranch_scc0 .LBB0_169
	s_and_b64 vcc, exec, s[28:29]
	s_cbranch_vccz .LBB0_172
	s_barrier

.LBB0_243:
	s_add_u32 s34, s44, 0xfff80080
	s_addc_u32 s35, s45, -1
	s_add_i32 s52, 0, 0x10000
	s_cmp_eq_u32 vcc_hi, 28
	s_cselect_b32 s47, s36, s35
	s_cselect_b32 s46, s37, s34
	s_cselect_b32 s35, s55, vcc_lo
	s_cselect_b32 s34, s57, s63
	s_add_i32 s68, 0, 0x14000
	v_add_u32_e32 v144, s52, v155
	v_add_u32_e32 v180, s68, v155
	ds_read_b128 v[132:135], v144
	ds_read_b128 v[136:139], v144 offset:1024
	ds_read_b128 v[140:143], v144 offset:2048
	ds_read_b128 v[144:147], v144 offset:3072
	ds_read_b128 v[176:179], v180
	ds_read_b128 v[182:185], v180 offset:1024
	ds_read_b128 v[186:189], v180 offset:2048
	ds_read_b128 v[190:193], v180 offset:3072
	v_lshl_add_u64 v[218:219], s[44:45], 0, v[172:173]
	s_add_i32 m0, s69, 0xc000
	ds_read_b128 v[194:197], v181
	ds_read_b128 v[198:201], v181 offset:1024
	ds_read_b128 v[202:205], v181 offset:2048
	ds_read_b128 v[206:209], v181 offset:3072
	ds_read_b128 v[210:213], v181 offset:4096
	ds_read_b128 v[214:217], v181 offset:5120
	ds_read_b128 v[228:231], v181 offset:6144
	ds_read_b128 v[232:235], v181 offset:7168
	global_load_lds_dwordx4 v[218:219], off
	v_lshl_add_u64 v[218:219], s[44:45], 0, v[174:175]
	s_add_i32 m0, s69, 0xe000
	s_nop 0
	global_load_lds_dwordx4 v[218:219], off
	s_waitcnt vmcnt(8)
	s_waitcnt lgkmcnt(0)
	s_barrier
	s_setprio 1
	v_mfma_f32_16x16x32_bf16 v[128:131], v[132:135], v[194:197], v[128:131]
	v_mfma_f32_16x16x32_bf16 v[128:131], v[136:139], v[198:201], v[128:131]
	v_mfma_f32_16x16x32_bf16 v[112:115], v[132:135], v[202:205], v[112:115]
	v_mfma_f32_16x16x32_bf16 v[112:115], v[136:139], v[206:209], v[112:115]
	v_mfma_f32_16x16x32_bf16 v[96:99], v[132:135], v[210:213], v[96:99]
	v_mfma_f32_16x16x32_bf16 v[96:99], v[136:139], v[214:217], v[96:99]
	v_mfma_f32_16x16x32_bf16 v[80:83], v[132:135], v[228:231], v[80:83]
	v_mfma_f32_16x16x32_bf16 v[80:83], v[136:139], v[232:235], v[80:83]
	v_mfma_f32_16x16x32_bf16 v[76:79], v[140:143], v[228:231], v[76:79]
	v_mfma_f32_16x16x32_bf16 v[76:79], v[144:147], v[232:235], v[76:79]
	v_mfma_f32_16x16x32_bf16 v[92:95], v[140:143], v[210:213], v[92:95]
	v_mfma_f32_16x16x32_bf16 v[92:95], v[144:147], v[214:217], v[92:95]
	v_mfma_f32_16x16x32_bf16 v[108:111], v[140:143], v[202:205], v[108:111]
	v_mfma_f32_16x16x32_bf16 v[108:111], v[144:147], v[206:209], v[108:111]
	v_mfma_f32_16x16x32_bf16 v[124:127], v[140:143], v[194:197], v[124:127]
	v_mfma_f32_16x16x32_bf16 v[124:127], v[144:147], v[198:201], v[124:127]
	v_mfma_f32_16x16x32_bf16 v[120:123], v[176:179], v[194:197], v[120:123]
	v_mfma_f32_16x16x32_bf16 v[120:123], v[182:185], v[198:201], v[120:123]
	v_mfma_f32_16x16x32_bf16 v[104:107], v[176:179], v[202:205], v[104:107]
	v_mfma_f32_16x16x32_bf16 v[104:107], v[182:185], v[206:209], v[104:107]
	v_mfma_f32_16x16x32_bf16 v[88:91], v[176:179], v[210:213], v[88:91]
	v_mfma_f32_16x16x32_bf16 v[88:91], v[182:185], v[214:217], v[88:91]
	v_mfma_f32_16x16x32_bf16 v[72:75], v[176:179], v[228:231], v[72:75]
	v_mfma_f32_16x16x32_bf16 v[72:75], v[182:185], v[232:235], v[72:75]
	v_mfma_f32_16x16x32_bf16 v[68:71], v[186:189], v[228:231], v[68:71]
	v_mfma_f32_16x16x32_bf16 v[68:71], v[190:193], v[232:235], v[68:71]
	v_mfma_f32_16x16x32_bf16 v[84:87], v[186:189], v[210:213], v[84:87]
	v_mfma_f32_16x16x32_bf16 v[84:87], v[190:193], v[214:217], v[84:87]
	v_mfma_f32_16x16x32_bf16 v[100:103], v[186:189], v[202:205], v[100:103]
	v_mfma_f32_16x16x32_bf16 v[100:103], v[190:193], v[206:209], v[100:103]
	v_mfma_f32_16x16x32_bf16 v[116:119], v[186:189], v[194:197], v[116:119]
	v_mfma_f32_16x16x32_bf16 v[116:119], v[190:193], v[198:201], v[116:119]
	s_setprio 0
	s_barrier
	s_add_i32 s52, s52, s2
	v_lshl_add_u64 v[218:219], s[34:35], 0, v[150:151]
	s_mov_b32 m0, s52
	ds_read_b128 v[194:197], v181 offset:16384
	ds_read_b128 v[198:201], v181 offset:17408
	ds_read_b128 v[202:205], v181 offset:18432
	ds_read_b128 v[206:209], v181 offset:19456
	ds_read_b128 v[210:213], v181 offset:20480
	ds_read_b128 v[214:217], v181 offset:21504
	ds_read_b128 v[228:231], v181 offset:22528
	ds_read_b128 v[232:235], v181 offset:23552
	global_load_lds_dwordx4 v[218:219], off
	s_add_i32 m0, s52, 0x2000
	s_add_u32 s52, s34, 0x4000
	v_lshl_add_u64 v[218:219], s[34:35], 0, v[0:1]
	s_addc_u32 s53, s35, 0
	s_add_i32 s68, s68, s2
	global_load_lds_dwordx4 v[218:219], off
	v_lshl_add_u64 v[218:219], s[52:53], 0, v[150:151]
	s_mov_b32 m0, s68
	v_lshl_add_u64 v[236:237], s[46:47], 0, v[148:149]
	global_load_lds_dwordx4 v[218:219], off
	v_lshl_add_u64 v[218:219], s[52:53], 0, v[0:1]
	s_add_i32 m0, s68, 0x2000
	s_nop 0
	global_load_lds_dwordx4 v[218:219], off
	v_lshl_add_u64 v[218:219], s[46:47], 0, v[152:153]
	s_mov_b32 m0, s69
	s_nop 0
	global_load_lds_dwordx4 v[218:219], off
	s_mov_b32 m0, s71
	s_nop 0
	global_load_lds_dwordx4 v[236:237], off
	s_waitcnt vmcnt(8)
	s_waitcnt lgkmcnt(0)
	s_barrier
	s_setprio 1
	v_mfma_f32_16x16x32_bf16 v[64:67], v[132:135], v[194:197], v[64:67]
	v_mfma_f32_16x16x32_bf16 v[64:67], v[136:139], v[198:201], v[64:67]
	v_mfma_f32_16x16x32_bf16 v[48:51], v[132:135], v[202:205], v[48:51]
	v_mfma_f32_16x16x32_bf16 v[48:51], v[136:139], v[206:209], v[48:51]
	v_mfma_f32_16x16x32_bf16 v[32:35], v[132:135], v[210:213], v[32:35]
	v_mfma_f32_16x16x32_bf16 v[32:35], v[136:139], v[214:217], v[32:35]
	v_mfma_f32_16x16x32_bf16 v[16:19], v[132:135], v[228:231], v[16:19]
	v_mfma_f32_16x16x32_bf16 v[16:19], v[136:139], v[232:235], v[16:19]
	v_mfma_f32_16x16x32_bf16 v[12:15], v[140:143], v[228:231], v[12:15]
	v_mfma_f32_16x16x32_bf16 v[12:15], v[144:147], v[232:235], v[12:15]
	v_mfma_f32_16x16x32_bf16 v[28:31], v[140:143], v[210:213], v[28:31]
	v_mfma_f32_16x16x32_bf16 v[28:31], v[144:147], v[214:217], v[28:31]
	v_mfma_f32_16x16x32_bf16 v[44:47], v[140:143], v[202:205], v[44:47]
	v_mfma_f32_16x16x32_bf16 v[44:47], v[144:147], v[206:209], v[44:47]
	v_mfma_f32_16x16x32_bf16 v[60:63], v[140:143], v[194:197], v[60:63]
	v_mfma_f32_16x16x32_bf16 v[60:63], v[144:147], v[198:201], v[60:63]
	v_mfma_f32_16x16x32_bf16 v[56:59], v[176:179], v[194:197], v[56:59]
	v_mfma_f32_16x16x32_bf16 v[56:59], v[182:185], v[198:201], v[56:59]
	v_mfma_f32_16x16x32_bf16 v[40:43], v[176:179], v[202:205], v[40:43]
	v_mfma_f32_16x16x32_bf16 v[40:43], v[182:185], v[206:209], v[40:43]
	v_mfma_f32_16x16x32_bf16 v[24:27], v[176:179], v[210:213], v[24:27]
	v_mfma_f32_16x16x32_bf16 v[24:27], v[182:185], v[214:217], v[24:27]
	v_mfma_f32_16x16x32_bf16 v[8:11], v[176:179], v[228:231], v[8:11]
	v_mfma_f32_16x16x32_bf16 v[8:11], v[182:185], v[232:235], v[8:11]
	v_mfma_f32_16x16x32_bf16 v[4:7], v[186:189], v[228:231], v[4:7]
	v_mfma_f32_16x16x32_bf16 v[4:7], v[190:193], v[232:235], v[4:7]
	v_mfma_f32_16x16x32_bf16 v[20:23], v[186:189], v[210:213], v[20:23]
	v_mfma_f32_16x16x32_bf16 v[20:23], v[190:193], v[214:217], v[20:23]
	v_mfma_f32_16x16x32_bf16 v[36:39], v[186:189], v[202:205], v[36:39]
	v_mfma_f32_16x16x32_bf16 v[36:39], v[190:193], v[206:209], v[36:39]
	v_mfma_f32_16x16x32_bf16 v[52:55], v[186:189], v[194:197], v[52:55]
	v_mfma_f32_16x16x32_bf16 v[52:55], v[190:193], v[198:201], v[52:55]
	s_setprio 0
	s_barrier
	s_add_i32 s52, 0, 0x18000
	s_add_i32 s53, 0, 0x1c000
	v_add_u32_e32 v144, s52, v155
	v_add_u32_e32 v180, s53, v155
	ds_read_b128 v[132:135], v144
	ds_read_b128 v[136:139], v144 offset:1024
	ds_read_b128 v[140:143], v144 offset:2048
	ds_read_b128 v[144:147], v144 offset:3072
	ds_read_b128 v[176:179], v180
	ds_read_b128 v[182:185], v180 offset:1024
	ds_read_b128 v[186:189], v180 offset:2048
	ds_read_b128 v[190:193], v180 offset:3072
	s_add_u32 s46, s46, 0x80000
	s_addc_u32 s47, s47, 0
	s_mov_b32 m0, s88
	v_lshl_add_u64 v[238:239], s[46:47], 0, v[152:153]
	ds_read_b128 v[194:197], v181 offset:32768
	ds_read_b128 v[198:201], v181 offset:33792
	ds_read_b128 v[202:205], v181 offset:34816
	ds_read_b128 v[206:209], v181 offset:35840
	ds_read_b128 v[210:213], v181 offset:36864
	ds_read_b128 v[214:217], v181 offset:37888
	ds_read_b128 v[228:231], v181 offset:38912
	ds_read_b128 v[232:235], v181 offset:39936
	global_load_lds_dwordx4 v[238:239], off
	v_lshl_add_u64 v[238:239], s[46:47], 0, v[148:149]
	s_mov_b32 m0, s96
	s_nop 0
	global_load_lds_dwordx4 v[238:239], off
	s_waitcnt vmcnt(8)
	s_waitcnt lgkmcnt(0)
	s_barrier
	s_setprio 1
	v_mfma_f32_16x16x32_bf16 v[128:131], v[132:135], v[194:197], v[128:131]
	v_mfma_f32_16x16x32_bf16 v[128:131], v[136:139], v[198:201], v[128:131]
	v_mfma_f32_16x16x32_bf16 v[112:115], v[132:135], v[202:205], v[112:115]
	v_mfma_f32_16x16x32_bf16 v[112:115], v[136:139], v[206:209], v[112:115]
	v_mfma_f32_16x16x32_bf16 v[96:99], v[132:135], v[210:213], v[96:99]
	v_mfma_f32_16x16x32_bf16 v[96:99], v[136:139], v[214:217], v[96:99]
	v_mfma_f32_16x16x32_bf16 v[80:83], v[132:135], v[228:231], v[80:83]
	v_mfma_f32_16x16x32_bf16 v[80:83], v[136:139], v[232:235], v[80:83]
	v_mfma_f32_16x16x32_bf16 v[76:79], v[140:143], v[228:231], v[76:79]
	v_mfma_f32_16x16x32_bf16 v[76:79], v[144:147], v[232:235], v[76:79]
	v_mfma_f32_16x16x32_bf16 v[92:95], v[140:143], v[210:213], v[92:95]
	v_mfma_f32_16x16x32_bf16 v[92:95], v[144:147], v[214:217], v[92:95]
	v_mfma_f32_16x16x32_bf16 v[108:111], v[140:143], v[202:205], v[108:111]
	v_mfma_f32_16x16x32_bf16 v[108:111], v[144:147], v[206:209], v[108:111]
	v_mfma_f32_16x16x32_bf16 v[124:127], v[140:143], v[194:197], v[124:127]
	v_mfma_f32_16x16x32_bf16 v[124:127], v[144:147], v[198:201], v[124:127]
	v_mfma_f32_16x16x32_bf16 v[120:123], v[176:179], v[194:197], v[120:123]
	v_mfma_f32_16x16x32_bf16 v[120:123], v[182:185], v[198:201], v[120:123]
	v_mfma_f32_16x16x32_bf16 v[104:107], v[176:179], v[202:205], v[104:107]
	v_mfma_f32_16x16x32_bf16 v[104:107], v[182:185], v[206:209], v[104:107]
	v_mfma_f32_16x16x32_bf16 v[88:91], v[176:179], v[210:213], v[88:91]
	v_mfma_f32_16x16x32_bf16 v[88:91], v[182:185], v[214:217], v[88:91]
	v_mfma_f32_16x16x32_bf16 v[72:75], v[176:179], v[228:231], v[72:75]
	v_mfma_f32_16x16x32_bf16 v[72:75], v[182:185], v[232:235], v[72:75]
	v_mfma_f32_16x16x32_bf16 v[68:71], v[186:189], v[228:231], v[68:71]
	v_mfma_f32_16x16x32_bf16 v[68:71], v[190:193], v[232:235], v[68:71]
	v_mfma_f32_16x16x32_bf16 v[84:87], v[186:189], v[210:213], v[84:87]
	v_mfma_f32_16x16x32_bf16 v[84:87], v[190:193], v[214:217], v[84:87]
	v_mfma_f32_16x16x32_bf16 v[100:103], v[186:189], v[202:205], v[100:103]
	v_mfma_f32_16x16x32_bf16 v[100:103], v[190:193], v[206:209], v[100:103]
	v_mfma_f32_16x16x32_bf16 v[116:119], v[186:189], v[194:197], v[116:119]
	v_mfma_f32_16x16x32_bf16 v[116:119], v[190:193], v[198:201], v[116:119]
	s_setprio 0
	s_barrier
	s_add_u32 s46, s34, 0x70000
	s_addc_u32 s47, s35, 0
	s_add_i32 s52, s52, s2
	v_lshl_add_u64 v[238:239], s[46:47], 0, v[150:151]
	s_mov_b32 m0, s52
	ds_read_b128 v[194:197], v181 offset:49152
	ds_read_b128 v[198:201], v181 offset:50176
	ds_read_b128 v[202:205], v181 offset:51200
	ds_read_b128 v[206:209], v181 offset:52224
	ds_read_b128 v[210:213], v181 offset:53248
	ds_read_b128 v[214:217], v181 offset:54272
	ds_read_b128 v[228:231], v181 offset:55296
	ds_read_b128 v[232:235], v181 offset:56320
	global_load_lds_dwordx4 v[238:239], off
	s_add_i32 m0, s52, 0x2000
	s_add_u32 s34, s34, 0x74000
	v_lshl_add_u64 v[238:239], s[46:47], 0, v[0:1]
	s_addc_u32 s35, s35, 0
	s_add_i32 s46, s53, s2
	global_load_lds_dwordx4 v[238:239], off
	v_lshl_add_u64 v[238:239], s[34:35], 0, v[150:151]
	s_mov_b32 m0, s46
	v_lshl_add_u64 v[218:219], v[218:219], 0, s[14:15]
	global_load_lds_dwordx4 v[238:239], off
	v_lshl_add_u64 v[238:239], s[34:35], 0, v[0:1]
	s_add_i32 m0, s46, 0x2000
	s_nop 0
	global_load_lds_dwordx4 v[238:239], off
	s_mov_b32 m0, s97
	s_nop 0
	global_load_lds_dwordx4 v[218:219], off
	v_lshl_add_u64 v[218:219], v[236:237], 0, s[14:15]
	s_mov_b32 m0, s76
	s_nop 0
	global_load_lds_dwordx4 v[218:219], off
	s_waitcnt vmcnt(8)
	s_waitcnt lgkmcnt(0)
	s_barrier
	s_setprio 1
	v_mfma_f32_16x16x32_bf16 v[64:67], v[132:135], v[194:197], v[64:67]
	v_mfma_f32_16x16x32_bf16 v[64:67], v[136:139], v[198:201], v[64:67]
	v_mfma_f32_16x16x32_bf16 v[48:51], v[132:135], v[202:205], v[48:51]
	v_mfma_f32_16x16x32_bf16 v[48:51], v[136:139], v[206:209], v[48:51]
	v_mfma_f32_16x16x32_bf16 v[32:35], v[132:135], v[210:213], v[32:35]
	v_mfma_f32_16x16x32_bf16 v[32:35], v[136:139], v[214:217], v[32:35]
	v_mfma_f32_16x16x32_bf16 v[16:19], v[132:135], v[228:231], v[16:19]
	v_mfma_f32_16x16x32_bf16 v[16:19], v[136:139], v[232:235], v[16:19]
	v_mfma_f32_16x16x32_bf16 v[12:15], v[140:143], v[228:231], v[12:15]
	v_mfma_f32_16x16x32_bf16 v[12:15], v[144:147], v[232:235], v[12:15]
	v_mfma_f32_16x16x32_bf16 v[28:31], v[140:143], v[210:213], v[28:31]
	v_mfma_f32_16x16x32_bf16 v[28:31], v[144:147], v[214:217], v[28:31]
	v_mfma_f32_16x16x32_bf16 v[44:47], v[140:143], v[202:205], v[44:47]
	v_mfma_f32_16x16x32_bf16 v[44:47], v[144:147], v[206:209], v[44:47]
	v_mfma_f32_16x16x32_bf16 v[60:63], v[140:143], v[194:197], v[60:63]
	v_mfma_f32_16x16x32_bf16 v[60:63], v[144:147], v[198:201], v[60:63]
	v_mfma_f32_16x16x32_bf16 v[56:59], v[176:179], v[194:197], v[56:59]
	v_mfma_f32_16x16x32_bf16 v[56:59], v[182:185], v[198:201], v[56:59]
	v_mfma_f32_16x16x32_bf16 v[40:43], v[176:179], v[202:205], v[40:43]
	v_mfma_f32_16x16x32_bf16 v[40:43], v[182:185], v[206:209], v[40:43]
	v_mfma_f32_16x16x32_bf16 v[24:27], v[176:179], v[210:213], v[24:27]
	v_mfma_f32_16x16x32_bf16 v[24:27], v[182:185], v[214:217], v[24:27]
	v_mfma_f32_16x16x32_bf16 v[8:11], v[176:179], v[228:231], v[8:11]
	v_mfma_f32_16x16x32_bf16 v[8:11], v[182:185], v[232:235], v[8:11]
	v_mfma_f32_16x16x32_bf16 v[4:7], v[186:189], v[228:231], v[4:7]
	v_mfma_f32_16x16x32_bf16 v[4:7], v[190:193], v[232:235], v[4:7]
	v_mfma_f32_16x16x32_bf16 v[20:23], v[186:189], v[210:213], v[20:23]
	v_mfma_f32_16x16x32_bf16 v[20:23], v[190:193], v[214:217], v[20:23]
	v_mfma_f32_16x16x32_bf16 v[36:39], v[186:189], v[202:205], v[36:39]
	v_mfma_f32_16x16x32_bf16 v[36:39], v[190:193], v[206:209], v[36:39]
	v_mfma_f32_16x16x32_bf16 v[52:55], v[186:189], v[194:197], v[52:55]
	v_mfma_f32_16x16x32_bf16 v[52:55], v[190:193], v[198:201], v[52:55]
	s_setprio 0
	s_barrier
	s_add_i32 vcc_hi, vcc_hi, 2
	s_add_u32 s63, s63, 0xe0000
	s_addc_u32 vcc_lo, vcc_lo, 0
	s_add_u32 s44, s44, 0x100
	s_addc_u32 s45, s45, 0
	s_cmp_gt_u32 vcc_hi, 29
	s_cbranch_scc0 .LBB0_243
	s_and_b64 vcc, exec, s[28:29]
	s_cbranch_vccz .LBB0_246
	s_barrier

.LBB0_559:
	s_add_i32 vcc_lo, s34, 2
	s_add_u32 s35, s42, 0x80
	s_addc_u32 s52, s43, 0
	s_add_i32 s53, 0, 0x10000
	s_cmp_eq_u32 s77, s34
	s_cselect_b32 s57, s51, s52
	s_cselect_b32 s56, s50, s35
	s_cselect_b32 s35, s36, s97
	s_cselect_b32 s34, s37, s49
	s_add_i32 s68, 0, 0x14000
	v_add_u32_e32 v136, s53, v200
	v_add_u32_e32 v186, s68, v200
	ds_read_b128 v[116:119], v136
	ds_read_b128 v[120:123], v136 offset:1024
	ds_read_b128 v[124:127], v136 offset:2048
	ds_read_b128 v[136:139], v136 offset:3072
	ds_read_b128 v[148:151], v186
	ds_read_b128 v[152:155], v186 offset:1024
	ds_read_b128 v[182:185], v186 offset:2048
	ds_read_b128 v[186:189], v186 offset:3072
	v_lshl_add_u64 v[198:199], s[42:43], 0, v[178:179]
	s_add_i32 m0, s59, 0xc000
	ds_read_b128 v[190:193], v202
	ds_read_b128 v[194:197], v202 offset:1024
	ds_read_b128 v[204:207], v202 offset:2048
	ds_read_b128 v[208:211], v202 offset:3072
	ds_read_b128 v[212:215], v202 offset:4096
	ds_read_b128 v[216:219], v202 offset:5120
	ds_read_b128 v[228:231], v202 offset:6144
	ds_read_b128 v[232:235], v202 offset:7168
	global_load_lds_dwordx4 v[198:199], off
	v_lshl_add_u64 v[198:199], s[42:43], 0, v[180:181]
	s_add_i32 m0, s59, 0xe000
	s_nop 0
	global_load_lds_dwordx4 v[198:199], off
	s_waitcnt vmcnt(8)
	s_waitcnt lgkmcnt(0)
	s_barrier
	s_setprio 1
	v_mfma_f32_16x16x32_bf16 v[144:147], v[116:119], v[190:193], v[144:147]
	v_mfma_f32_16x16x32_bf16 v[144:147], v[120:123], v[194:197], v[144:147]
	v_mfma_f32_16x16x32_bf16 v[112:115], v[116:119], v[204:207], v[112:115]
	v_mfma_f32_16x16x32_bf16 v[112:115], v[120:123], v[208:211], v[112:115]
	v_mfma_f32_16x16x32_bf16 v[96:99], v[116:119], v[212:215], v[96:99]
	v_mfma_f32_16x16x32_bf16 v[96:99], v[120:123], v[216:219], v[96:99]
	v_mfma_f32_16x16x32_bf16 v[80:83], v[116:119], v[228:231], v[80:83]
	v_mfma_f32_16x16x32_bf16 v[80:83], v[120:123], v[232:235], v[80:83]
	v_mfma_f32_16x16x32_bf16 v[76:79], v[124:127], v[228:231], v[76:79]
	v_mfma_f32_16x16x32_bf16 v[76:79], v[136:139], v[232:235], v[76:79]
	v_mfma_f32_16x16x32_bf16 v[92:95], v[124:127], v[212:215], v[92:95]
	v_mfma_f32_16x16x32_bf16 v[92:95], v[136:139], v[216:219], v[92:95]
	v_mfma_f32_16x16x32_bf16 v[108:111], v[124:127], v[204:207], v[108:111]
	v_mfma_f32_16x16x32_bf16 v[108:111], v[136:139], v[208:211], v[108:111]
	v_mfma_f32_16x16x32_bf16 v[140:143], v[124:127], v[190:193], v[140:143]
	v_mfma_f32_16x16x32_bf16 v[140:143], v[136:139], v[194:197], v[140:143]
	v_mfma_f32_16x16x32_bf16 v[132:135], v[148:151], v[190:193], v[132:135]
	v_mfma_f32_16x16x32_bf16 v[132:135], v[152:155], v[194:197], v[132:135]
	v_mfma_f32_16x16x32_bf16 v[104:107], v[148:151], v[204:207], v[104:107]
	v_mfma_f32_16x16x32_bf16 v[104:107], v[152:155], v[208:211], v[104:107]
	v_mfma_f32_16x16x32_bf16 v[88:91], v[148:151], v[212:215], v[88:91]
	v_mfma_f32_16x16x32_bf16 v[88:91], v[152:155], v[216:219], v[88:91]
	v_mfma_f32_16x16x32_bf16 v[72:75], v[148:151], v[228:231], v[72:75]
	v_mfma_f32_16x16x32_bf16 v[72:75], v[152:155], v[232:235], v[72:75]
	v_mfma_f32_16x16x32_bf16 v[68:71], v[182:185], v[228:231], v[68:71]
	v_mfma_f32_16x16x32_bf16 v[68:71], v[186:189], v[232:235], v[68:71]
	v_mfma_f32_16x16x32_bf16 v[84:87], v[182:185], v[212:215], v[84:87]
	v_mfma_f32_16x16x32_bf16 v[84:87], v[186:189], v[216:219], v[84:87]
	v_mfma_f32_16x16x32_bf16 v[100:103], v[182:185], v[204:207], v[100:103]
	v_mfma_f32_16x16x32_bf16 v[100:103], v[186:189], v[208:211], v[100:103]
	v_mfma_f32_16x16x32_bf16 v[128:131], v[182:185], v[190:193], v[128:131]
	v_mfma_f32_16x16x32_bf16 v[128:131], v[186:189], v[194:197], v[128:131]
	s_setprio 0
	s_barrier
	s_add_i32 s52, s53, s58
	v_lshl_add_u64 v[198:199], s[34:35], 0, v[174:175]
	s_mov_b32 m0, s52
	ds_read_b128 v[190:193], v202 offset:16384
	ds_read_b128 v[194:197], v202 offset:17408
	ds_read_b128 v[204:207], v202 offset:18432
	ds_read_b128 v[208:211], v202 offset:19456
	ds_read_b128 v[212:215], v202 offset:20480
	ds_read_b128 v[216:219], v202 offset:21504
	ds_read_b128 v[228:231], v202 offset:22528
	ds_read_b128 v[232:235], v202 offset:23552
	global_load_lds_dwordx4 v[198:199], off
	s_add_i32 m0, s52, 0x2000
	s_add_u32 s52, s34, 0x4000
	v_lshl_add_u64 v[198:199], s[34:35], 0, v[0:1]
	s_addc_u32 s53, s35, 0
	s_add_i32 s68, s68, s58
	global_load_lds_dwordx4 v[198:199], off
	v_lshl_add_u64 v[198:199], s[52:53], 0, v[174:175]
	s_mov_b32 m0, s68
	v_lshl_add_u64 v[236:237], s[56:57], 0, v[172:173]
	global_load_lds_dwordx4 v[198:199], off
	v_lshl_add_u64 v[198:199], s[52:53], 0, v[0:1]
	s_add_i32 m0, s68, 0x2000
	s_nop 0
	global_load_lds_dwordx4 v[198:199], off
	v_lshl_add_u64 v[198:199], s[56:57], 0, v[176:177]
	s_mov_b32 m0, s59
	s_nop 0
	global_load_lds_dwordx4 v[198:199], off
	s_mov_b32 m0, s60
	s_nop 0
	global_load_lds_dwordx4 v[236:237], off
	s_waitcnt vmcnt(8)
	s_waitcnt lgkmcnt(0)
	s_barrier
	s_setprio 1
	v_mfma_f32_16x16x32_bf16 v[64:67], v[116:119], v[190:193], v[64:67]
	v_mfma_f32_16x16x32_bf16 v[64:67], v[120:123], v[194:197], v[64:67]
	v_mfma_f32_16x16x32_bf16 v[48:51], v[116:119], v[204:207], v[48:51]
	v_mfma_f32_16x16x32_bf16 v[48:51], v[120:123], v[208:211], v[48:51]
	v_mfma_f32_16x16x32_bf16 v[32:35], v[116:119], v[212:215], v[32:35]
	v_mfma_f32_16x16x32_bf16 v[32:35], v[120:123], v[216:219], v[32:35]
	v_mfma_f32_16x16x32_bf16 v[16:19], v[116:119], v[228:231], v[16:19]
	v_mfma_f32_16x16x32_bf16 v[16:19], v[120:123], v[232:235], v[16:19]
	v_mfma_f32_16x16x32_bf16 v[12:15], v[124:127], v[228:231], v[12:15]
	v_mfma_f32_16x16x32_bf16 v[12:15], v[136:139], v[232:235], v[12:15]
	v_mfma_f32_16x16x32_bf16 v[28:31], v[124:127], v[212:215], v[28:31]
	v_mfma_f32_16x16x32_bf16 v[28:31], v[136:139], v[216:219], v[28:31]
	v_mfma_f32_16x16x32_bf16 v[44:47], v[124:127], v[204:207], v[44:47]
	v_mfma_f32_16x16x32_bf16 v[44:47], v[136:139], v[208:211], v[44:47]
	v_mfma_f32_16x16x32_bf16 v[60:63], v[124:127], v[190:193], v[60:63]
	v_mfma_f32_16x16x32_bf16 v[60:63], v[136:139], v[194:197], v[60:63]
	v_mfma_f32_16x16x32_bf16 v[56:59], v[148:151], v[190:193], v[56:59]
	v_mfma_f32_16x16x32_bf16 v[56:59], v[152:155], v[194:197], v[56:59]
	v_mfma_f32_16x16x32_bf16 v[40:43], v[148:151], v[204:207], v[40:43]
	v_mfma_f32_16x16x32_bf16 v[40:43], v[152:155], v[208:211], v[40:43]
	v_mfma_f32_16x16x32_bf16 v[24:27], v[148:151], v[212:215], v[24:27]
	v_mfma_f32_16x16x32_bf16 v[24:27], v[152:155], v[216:219], v[24:27]
	v_mfma_f32_16x16x32_bf16 v[8:11], v[148:151], v[228:231], v[8:11]
	v_mfma_f32_16x16x32_bf16 v[8:11], v[152:155], v[232:235], v[8:11]
	v_mfma_f32_16x16x32_bf16 v[4:7], v[182:185], v[228:231], v[4:7]
	v_mfma_f32_16x16x32_bf16 v[4:7], v[186:189], v[232:235], v[4:7]
	v_mfma_f32_16x16x32_bf16 v[20:23], v[182:185], v[212:215], v[20:23]
	v_mfma_f32_16x16x32_bf16 v[20:23], v[186:189], v[216:219], v[20:23]
	v_mfma_f32_16x16x32_bf16 v[36:39], v[182:185], v[204:207], v[36:39]
	v_mfma_f32_16x16x32_bf16 v[36:39], v[186:189], v[208:211], v[36:39]
	v_mfma_f32_16x16x32_bf16 v[52:55], v[182:185], v[190:193], v[52:55]
	v_mfma_f32_16x16x32_bf16 v[52:55], v[186:189], v[194:197], v[52:55]
	s_setprio 0
	s_barrier
	s_add_i32 s68, 0, 0x18000
	s_add_i32 vcc_hi, 0, 0x1c000
	v_add_u32_e32 v136, s68, v200
	v_add_u32_e32 v186, vcc_hi, v200
	ds_read_b128 v[116:119], v136
	ds_read_b128 v[120:123], v136 offset:1024
	ds_read_b128 v[124:127], v136 offset:2048
	ds_read_b128 v[136:139], v136 offset:3072
	ds_read_b128 v[148:151], v186
	ds_read_b128 v[152:155], v186 offset:1024
	ds_read_b128 v[182:185], v186 offset:2048
	ds_read_b128 v[186:189], v186 offset:3072
	s_add_u32 s52, s56, s26
	s_addc_u32 s53, s57, 0
	s_mov_b32 m0, s61
	v_lshl_add_u64 v[238:239], s[52:53], 0, v[176:177]
	ds_read_b128 v[190:193], v202 offset:32768
	ds_read_b128 v[194:197], v202 offset:33792
	ds_read_b128 v[204:207], v202 offset:34816
	ds_read_b128 v[208:211], v202 offset:35840
	ds_read_b128 v[212:215], v202 offset:36864
	ds_read_b128 v[216:219], v202 offset:37888
	ds_read_b128 v[228:231], v202 offset:38912
	ds_read_b128 v[232:235], v202 offset:39936
	global_load_lds_dwordx4 v[238:239], off
	v_lshl_add_u64 v[238:239], s[52:53], 0, v[172:173]
	s_mov_b32 m0, s62
	s_nop 0
	global_load_lds_dwordx4 v[238:239], off
	s_waitcnt vmcnt(8)
	s_waitcnt lgkmcnt(0)
	s_barrier
	s_setprio 1
	v_mfma_f32_16x16x32_bf16 v[144:147], v[116:119], v[190:193], v[144:147]
	v_mfma_f32_16x16x32_bf16 v[144:147], v[120:123], v[194:197], v[144:147]
	v_mfma_f32_16x16x32_bf16 v[112:115], v[116:119], v[204:207], v[112:115]
	v_mfma_f32_16x16x32_bf16 v[112:115], v[120:123], v[208:211], v[112:115]
	v_mfma_f32_16x16x32_bf16 v[96:99], v[116:119], v[212:215], v[96:99]
	v_mfma_f32_16x16x32_bf16 v[96:99], v[120:123], v[216:219], v[96:99]
	v_mfma_f32_16x16x32_bf16 v[80:83], v[116:119], v[228:231], v[80:83]
	v_mfma_f32_16x16x32_bf16 v[80:83], v[120:123], v[232:235], v[80:83]
	v_mfma_f32_16x16x32_bf16 v[76:79], v[124:127], v[228:231], v[76:79]
	v_mfma_f32_16x16x32_bf16 v[76:79], v[136:139], v[232:235], v[76:79]
	v_mfma_f32_16x16x32_bf16 v[92:95], v[124:127], v[212:215], v[92:95]
	v_mfma_f32_16x16x32_bf16 v[92:95], v[136:139], v[216:219], v[92:95]
	v_mfma_f32_16x16x32_bf16 v[108:111], v[124:127], v[204:207], v[108:111]
	v_mfma_f32_16x16x32_bf16 v[108:111], v[136:139], v[208:211], v[108:111]
	v_mfma_f32_16x16x32_bf16 v[140:143], v[124:127], v[190:193], v[140:143]
	v_mfma_f32_16x16x32_bf16 v[140:143], v[136:139], v[194:197], v[140:143]
	v_mfma_f32_16x16x32_bf16 v[132:135], v[148:151], v[190:193], v[132:135]
	v_mfma_f32_16x16x32_bf16 v[132:135], v[152:155], v[194:197], v[132:135]
	v_mfma_f32_16x16x32_bf16 v[104:107], v[148:151], v[204:207], v[104:107]
	v_mfma_f32_16x16x32_bf16 v[104:107], v[152:155], v[208:211], v[104:107]
	v_mfma_f32_16x16x32_bf16 v[88:91], v[148:151], v[212:215], v[88:91]
	v_mfma_f32_16x16x32_bf16 v[88:91], v[152:155], v[216:219], v[88:91]
	v_mfma_f32_16x16x32_bf16 v[72:75], v[148:151], v[228:231], v[72:75]
	v_mfma_f32_16x16x32_bf16 v[72:75], v[152:155], v[232:235], v[72:75]
	v_mfma_f32_16x16x32_bf16 v[68:71], v[182:185], v[228:231], v[68:71]
	v_mfma_f32_16x16x32_bf16 v[68:71], v[186:189], v[232:235], v[68:71]
	v_mfma_f32_16x16x32_bf16 v[84:87], v[182:185], v[212:215], v[84:87]
	v_mfma_f32_16x16x32_bf16 v[84:87], v[186:189], v[216:219], v[84:87]
	v_mfma_f32_16x16x32_bf16 v[100:103], v[182:185], v[204:207], v[100:103]
	v_mfma_f32_16x16x32_bf16 v[100:103], v[186:189], v[208:211], v[100:103]
	v_mfma_f32_16x16x32_bf16 v[128:131], v[182:185], v[190:193], v[128:131]
	v_mfma_f32_16x16x32_bf16 v[128:131], v[186:189], v[194:197], v[128:131]
	s_setprio 0
	s_barrier
	s_add_u32 s52, s34, 0x40000
	s_addc_u32 s53, s35, 0
	s_add_i32 s56, s68, s58
	v_lshl_add_u64 v[238:239], s[52:53], 0, v[174:175]
	s_mov_b32 m0, s56
	ds_read_b128 v[190:193], v202 offset:49152
	ds_read_b128 v[194:197], v202 offset:50176
	ds_read_b128 v[204:207], v202 offset:51200
	ds_read_b128 v[208:211], v202 offset:52224
	ds_read_b128 v[212:215], v202 offset:53248
	ds_read_b128 v[216:219], v202 offset:54272
	ds_read_b128 v[228:231], v202 offset:55296
	ds_read_b128 v[232:235], v202 offset:56320
	global_load_lds_dwordx4 v[238:239], off
	s_add_i32 m0, s56, 0x2000
	s_add_u32 s34, s34, 0x44000
	v_lshl_add_u64 v[238:239], s[52:53], 0, v[0:1]
	s_addc_u32 s35, s35, 0
	s_add_i32 s52, vcc_hi, s58
	global_load_lds_dwordx4 v[238:239], off
	v_lshl_add_u64 v[238:239], s[34:35], 0, v[174:175]
	s_mov_b32 m0, s52
	v_lshl_add_u64 v[198:199], v[198:199], 0, s[14:15]
	global_load_lds_dwordx4 v[238:239], off
	v_lshl_add_u64 v[238:239], s[34:35], 0, v[0:1]
	s_add_i32 m0, s52, 0x2000
	s_nop 0
	global_load_lds_dwordx4 v[238:239], off
	s_mov_b32 m0, s71
	s_nop 0
	global_load_lds_dwordx4 v[198:199], off
	v_lshl_add_u64 v[198:199], v[236:237], 0, s[14:15]
	s_mov_b32 m0, s76
	s_nop 0
	global_load_lds_dwordx4 v[198:199], off
	s_waitcnt vmcnt(8)
	s_waitcnt lgkmcnt(0)
	s_barrier
	s_setprio 1
	v_mfma_f32_16x16x32_bf16 v[64:67], v[116:119], v[190:193], v[64:67]
	v_mfma_f32_16x16x32_bf16 v[64:67], v[120:123], v[194:197], v[64:67]
	v_mfma_f32_16x16x32_bf16 v[48:51], v[116:119], v[204:207], v[48:51]
	v_mfma_f32_16x16x32_bf16 v[48:51], v[120:123], v[208:211], v[48:51]
	v_mfma_f32_16x16x32_bf16 v[32:35], v[116:119], v[212:215], v[32:35]
	v_mfma_f32_16x16x32_bf16 v[32:35], v[120:123], v[216:219], v[32:35]
	v_mfma_f32_16x16x32_bf16 v[16:19], v[116:119], v[228:231], v[16:19]
	v_mfma_f32_16x16x32_bf16 v[16:19], v[120:123], v[232:235], v[16:19]
	v_mfma_f32_16x16x32_bf16 v[12:15], v[124:127], v[228:231], v[12:15]
	v_mfma_f32_16x16x32_bf16 v[12:15], v[136:139], v[232:235], v[12:15]
	v_mfma_f32_16x16x32_bf16 v[28:31], v[124:127], v[212:215], v[28:31]
	v_mfma_f32_16x16x32_bf16 v[28:31], v[136:139], v[216:219], v[28:31]
	v_mfma_f32_16x16x32_bf16 v[44:47], v[124:127], v[204:207], v[44:47]
	v_mfma_f32_16x16x32_bf16 v[44:47], v[136:139], v[208:211], v[44:47]
	v_mfma_f32_16x16x32_bf16 v[60:63], v[124:127], v[190:193], v[60:63]
	v_mfma_f32_16x16x32_bf16 v[60:63], v[136:139], v[194:197], v[60:63]
	v_mfma_f32_16x16x32_bf16 v[56:59], v[148:151], v[190:193], v[56:59]
	v_mfma_f32_16x16x32_bf16 v[56:59], v[152:155], v[194:197], v[56:59]
	v_mfma_f32_16x16x32_bf16 v[40:43], v[148:151], v[204:207], v[40:43]
	v_mfma_f32_16x16x32_bf16 v[40:43], v[152:155], v[208:211], v[40:43]
	v_mfma_f32_16x16x32_bf16 v[24:27], v[148:151], v[212:215], v[24:27]
	v_mfma_f32_16x16x32_bf16 v[24:27], v[152:155], v[216:219], v[24:27]
	v_mfma_f32_16x16x32_bf16 v[8:11], v[148:151], v[228:231], v[8:11]
	v_mfma_f32_16x16x32_bf16 v[8:11], v[152:155], v[232:235], v[8:11]
	v_mfma_f32_16x16x32_bf16 v[4:7], v[182:185], v[228:231], v[4:7]
	v_mfma_f32_16x16x32_bf16 v[4:7], v[186:189], v[232:235], v[4:7]
	v_mfma_f32_16x16x32_bf16 v[20:23], v[182:185], v[212:215], v[20:23]
	v_mfma_f32_16x16x32_bf16 v[20:23], v[186:189], v[216:219], v[20:23]
	v_mfma_f32_16x16x32_bf16 v[36:39], v[182:185], v[204:207], v[36:39]
	v_mfma_f32_16x16x32_bf16 v[36:39], v[186:189], v[208:211], v[36:39]
	v_mfma_f32_16x16x32_bf16 v[52:55], v[182:185], v[190:193], v[52:55]
	v_mfma_f32_16x16x32_bf16 v[52:55], v[186:189], v[194:197], v[52:55]
	s_setprio 0
	s_barrier
	s_add_u32 s49, s49, 0x80000
	s_addc_u32 s97, s97, 0
	s_add_u32 s42, s42, 0x100
	s_addc_u32 s43, s43, 0
	s_cmp_ge_u32 vcc_lo, s69
	s_mov_b32 s34, vcc_lo
	s_cbranch_scc0 .LBB0_559
	s_and_b64 vcc, exec, s[46:47]
	s_cbranch_vccz .LBB0_562
	s_barrier
